# grid barrier spin loops poll with s_sleep 4 instead of 1 (fewer outstanding device-scope polls on the generation word)
# speedup vs baseline: 1.0057x; 1.0057x over previous
; __global__ void __launch_bounds__(256, 2) fwd_megakernel(P p) {
;     ...
;     if (p.ws == nullptr) cgrid.sync();
.LBB0_11:
	s_sleep 4
	global_load_dword v3, v2, s[4:5] offset:32 sc1
	s_waitcnt vmcnt(0)
	v_and_b32_e32 v3, 0xffff0000, v3
	v_cmp_ne_u32_e32 vcc, v3, v1
	s_or_b64 s[6:7], vcc, s[6:7]
	s_andn2_b64 exec, exec, s[6:7]
	s_cbranch_execnz .LBB0_11

; DEVI unsigned xb_ld(unsigned* p) { return __hip_atomic_load(p, __ATOMIC_RELAXED, __HIP_MEMORY_SCOPE_AGENT); }
; DEVI void xb_complete(XB& b) {
;     const unsigned G = gridDim.x;
;     unsigned sum, cnt, mine, sp = 0u;
;     for (;;) {
;         sum = 0u; cnt = 0u; mine = 0u;
; #pragma unroll
;         for (unsigned j = 0; j < 16; ++j) { const unsigned c = xb_ld(&b.bar[XB_XCNT(j)]); sum += c; cnt += (c > 0u) ? 1u : 0u; mine = (j == b.x) ? c : mine; }
;         if (sum == G) break;
;         __builtin_amdgcn_s_sleep(1);
;         if ((++sp & 255u) == 0u) { if (xb_ld(&b.bar[XB_TMO])) break; if (sp > XB_SPIN_CAP) { atomicAdd(&b.bar[XB_TMO], 1u); break; } }
;     }
.LBB0_33:
	global_load_dword v16, v17, s[4:5] sc1
	global_load_dword v3, v17, s[6:7] sc1
	global_load_dword v4, v17, s[8:9] sc1
	global_load_dword v5, v17, s[10:11] sc1
	global_load_dword v6, v17, s[12:13] sc1
	global_load_dword v7, v17, s[14:15] sc1
	global_load_dword v8, v17, s[16:17] sc1
	global_load_dword v10, v17, s[18:19] sc1
	global_load_dword v11, v17, s[20:21] sc1
	global_load_dword v12, v17, s[22:23] sc1
	global_load_dword v13, v17, s[24:25] sc1
	global_load_dword v14, v17, s[28:29] sc1
	global_load_dword v15, v17, s[30:31] sc1
	global_load_dword v1, v17, s[34:35] sc1
	global_load_dword v2, v17, s[36:37] sc1
	global_load_dword v0, v17, s[42:43] sc1
	s_mov_b64 s[44:45], -1
	s_mov_b64 s[54:55], -1
	s_waitcnt vmcnt(14)
	v_add_u32_e32 v18, v3, v16
	s_waitcnt vmcnt(13)
	v_add_u32_e32 v18, v18, v4
	s_waitcnt vmcnt(12)
	v_add_u32_e32 v18, v18, v5
	s_waitcnt vmcnt(11)
	v_add_u32_e32 v18, v18, v6
	s_waitcnt vmcnt(10)
	v_add_u32_e32 v18, v18, v7
	s_waitcnt vmcnt(9)
	v_add_u32_e32 v18, v18, v8
	s_waitcnt vmcnt(8)
	v_add_u32_e32 v18, v18, v10
	s_waitcnt vmcnt(7)
	v_add_u32_e32 v18, v18, v11
	s_waitcnt vmcnt(6)
	v_add_u32_e32 v18, v18, v12
	s_waitcnt vmcnt(5)
	v_add_u32_e32 v18, v18, v13
	s_waitcnt vmcnt(4)
	v_add_u32_e32 v18, v18, v14
	s_waitcnt vmcnt(3)
	v_add_u32_e32 v18, v18, v15
	s_waitcnt vmcnt(2)
	v_add_u32_e32 v18, v18, v1
	s_waitcnt vmcnt(1)
	v_add_u32_e32 v18, v18, v2
	s_waitcnt vmcnt(0)
	v_add_u32_e32 v18, v18, v0
	v_cmp_eq_u32_e32 vcc, s27, v18
	s_cbranch_vccnz .LBB0_32
	s_and_b32 s33, s26, 0xff
	s_cmp_eq_u32 s33, 0
	s_mov_b64 s[58:59], -1
	s_sleep 4
	s_cbranch_scc1 .LBB0_37
	s_and_b64 vcc, exec, s[58:59]
	s_cbranch_vccz .LBB0_32

; DEVI unsigned xb_ld(unsigned* p) { return __hip_atomic_load(p, __ATOMIC_RELAXED, __HIP_MEMORY_SCOPE_AGENT); }
; DEVI unsigned xb_add(unsigned* p, unsigned v) { return __hip_atomic_fetch_add(p, v, __ATOMIC_RELAXED, __HIP_MEMORY_SCOPE_AGENT); }
; #define XB_SPIN(cond, bar) do { unsigned _sp = 0; while (cond) { __builtin_amdgcn_s_sleep(1); \
;     if ((++_sp & 255u) == 0u) { if (xb_ld(&(bar)[XB_TMO])) break; if (_sp > XB_SPIN_CAP) { atomicAdd(&(bar)[XB_TMO], 1u); break; } } } } while (0)
; DEVI void gsync(XB& b) {
;     ...
;             const unsigned og = xb_add(&bar[XB_TOP], 1u);
;             const unsigned tg = og / nx;
;             if (og + 1u == (tg + 1u) * nx) xb_add(&bar[XB_TOPGEN], 1u);
;             else XB_SPIN(xb_ld(&bar[XB_TOPGEN]) == tg, bar);
.LBB0_50:
	s_and_b32 s18, s22, 0xff
	s_mov_b64 s[16:17], -1
	s_cmp_lg_u32 s18, 0
	s_mov_b64 s[20:21], -1
	s_sleep 4
	s_cbranch_scc0 .LBB0_53
	s_and_b64 vcc, exec, s[20:21]
	s_cbranch_vccz .LBB0_49

; DEVI unsigned xb_ld(unsigned* p) { return __hip_atomic_load(p, __ATOMIC_RELAXED, __HIP_MEMORY_SCOPE_AGENT); }
; #define XB_SPIN(cond, bar) do { unsigned _sp = 0; while (cond) { __builtin_amdgcn_s_sleep(1); \
;     if ((++_sp & 255u) == 0u) { if (xb_ld(&(bar)[XB_TMO])) break; if (_sp > XB_SPIN_CAP) { atomicAdd(&(bar)[XB_TMO], 1u); break; } } } } while (0)
; DEVI void gsync(XB& b) {
;     ...
;         } else {
;             XB_SPIN(xb_ld(&bar[XB_XGEN(b.x)]) == gen, bar);
.LBB0_67:
	s_and_b32 s18, s24, 0xff
	s_cmp_lg_u32 s18, 0
	s_mov_b64 s[20:21], -1
	s_sleep 4
	s_cbranch_scc0 .LBB0_70
	s_mov_b64 s[22:23], -1
	s_and_b64 vcc, exec, s[20:21]
	s_cbranch_vccz .LBB0_66

; DEVI unsigned xb_ld(unsigned* p) { return __hip_atomic_load(p, __ATOMIC_RELAXED, __HIP_MEMORY_SCOPE_AGENT); }
; DEVI void xb_complete(XB& b) {
;     const unsigned G = gridDim.x;
;     unsigned sum, cnt, mine, sp = 0u;
;     for (;;) {
;         sum = 0u; cnt = 0u; mine = 0u;
; #pragma unroll
;         for (unsigned j = 0; j < 16; ++j) { const unsigned c = xb_ld(&b.bar[XB_XCNT(j)]); sum += c; cnt += (c > 0u) ? 1u : 0u; mine = (j == b.x) ? c : mine; }
;         if (sum == G) break;
;         __builtin_amdgcn_s_sleep(1);
;         if ((++sp & 255u) == 0u) { if (xb_ld(&b.bar[XB_TMO])) break; if (sp > XB_SPIN_CAP) { atomicAdd(&b.bar[XB_TMO], 1u); break; } }
;     }
.LBB0_168:
	global_load_dword v15, v16, s[4:5] sc1
	global_load_dword v0, v16, s[6:7] sc1
	global_load_dword v1, v16, s[8:9] sc1
	global_load_dword v2, v16, s[10:11] sc1
	global_load_dword v3, v16, s[12:13] sc1
	global_load_dword v4, v16, s[14:15] sc1
	global_load_dword v5, v16, s[18:19] sc1
	global_load_dword v6, v16, s[20:21] sc1
	global_load_dword v7, v16, s[22:23] sc1
	global_load_dword v8, v16, s[24:25] sc1
	global_load_dword v9, v16, s[28:29] sc1
	global_load_dword v10, v16, s[34:35] sc1
	global_load_dword v11, v16, s[36:37] sc1
	global_load_dword v12, v16, s[40:41] sc1
	global_load_dword v13, v16, s[42:43] sc1
	global_load_dword v14, v16, s[44:45] sc1
	s_mov_b64 s[50:51], -1
	s_mov_b64 s[54:55], -1
	s_waitcnt vmcnt(14)
	v_add_u32_e32 v17, v0, v15
	s_waitcnt vmcnt(13)
	v_add_u32_e32 v17, v17, v1
	s_waitcnt vmcnt(12)
	v_add_u32_e32 v17, v17, v2
	s_waitcnt vmcnt(11)
	v_add_u32_e32 v17, v17, v3
	s_waitcnt vmcnt(10)
	v_add_u32_e32 v17, v17, v4
	s_waitcnt vmcnt(9)
	v_add_u32_e32 v17, v17, v5
	s_waitcnt vmcnt(8)
	v_add_u32_e32 v17, v17, v6
	s_waitcnt vmcnt(7)
	v_add_u32_e32 v17, v17, v7
	s_waitcnt vmcnt(6)
	v_add_u32_e32 v17, v17, v8
	s_waitcnt vmcnt(5)
	v_add_u32_e32 v17, v17, v9
	s_waitcnt vmcnt(4)
	v_add_u32_e32 v17, v17, v10
	s_waitcnt vmcnt(3)
	v_add_u32_e32 v17, v17, v11
	s_waitcnt vmcnt(2)
	v_add_u32_e32 v17, v17, v12
	s_waitcnt vmcnt(1)
	v_add_u32_e32 v17, v17, v13
	s_waitcnt vmcnt(0)
	v_add_u32_e32 v17, v17, v14
	v_cmp_eq_u32_e32 vcc, s27, v17
	s_cbranch_vccnz .LBB0_167
	s_and_b32 s17, s16, 0xff
	s_cmp_eq_u32 s17, 0
	s_mov_b64 s[58:59], -1
	s_sleep 4
	s_cbranch_scc1 .LBB0_172
	s_and_b64 vcc, exec, s[58:59]
	s_cbranch_vccz .LBB0_167

; DEVI unsigned xb_ld(unsigned* p) { return __hip_atomic_load(p, __ATOMIC_RELAXED, __HIP_MEMORY_SCOPE_AGENT); }
; DEVI unsigned xb_add(unsigned* p, unsigned v) { return __hip_atomic_fetch_add(p, v, __ATOMIC_RELAXED, __HIP_MEMORY_SCOPE_AGENT); }
; #define XB_SPIN(cond, bar) do { unsigned _sp = 0; while (cond) { __builtin_amdgcn_s_sleep(1); \
;     if ((++_sp & 255u) == 0u) { if (xb_ld(&(bar)[XB_TMO])) break; if (_sp > XB_SPIN_CAP) { atomicAdd(&(bar)[XB_TMO], 1u); break; } } } } while (0)
; DEVI void gsync(XB& b) {
;     ...
;             const unsigned og = xb_add(&bar[XB_TOP], 1u);
;             const unsigned tg = og / nx;
;             if (og + 1u == (tg + 1u) * nx) xb_add(&bar[XB_TOPGEN], 1u);
;             else XB_SPIN(xb_ld(&bar[XB_TOPGEN]) == tg, bar);
.LBB0_186:
	s_and_b32 s17, s16, 0xff
	s_mov_b64 s[18:19], -1
	s_cmp_lg_u32 s17, 0
	s_mov_b64 s[22:23], -1
	s_sleep 4
	s_cbranch_scc0 .LBB0_189
	s_and_b64 vcc, exec, s[22:23]
	s_cbranch_vccz .LBB0_185

; DEVI unsigned xb_ld(unsigned* p) { return __hip_atomic_load(p, __ATOMIC_RELAXED, __HIP_MEMORY_SCOPE_AGENT); }
; #define XB_SPIN(cond, bar) do { unsigned _sp = 0; while (cond) { __builtin_amdgcn_s_sleep(1); \
;     if ((++_sp & 255u) == 0u) { if (xb_ld(&(bar)[XB_TMO])) break; if (_sp > XB_SPIN_CAP) { atomicAdd(&(bar)[XB_TMO], 1u); break; } } } } while (0)
; DEVI void gsync(XB& b) {
;     ...
;         } else {
;             XB_SPIN(xb_ld(&bar[XB_XGEN(b.x)]) == gen, bar);
.LBB0_203:
	s_and_b32 s17, s16, 0xff
	s_cmp_lg_u32 s17, 0
	s_mov_b64 s[22:23], -1
	s_sleep 4
	s_cbranch_scc0 .LBB0_206
	s_mov_b64 s[24:25], -1
	s_and_b64 vcc, exec, s[22:23]
	s_cbranch_vccz .LBB0_202

; DEVI unsigned xb_ld(unsigned* p) { return __hip_atomic_load(p, __ATOMIC_RELAXED, __HIP_MEMORY_SCOPE_AGENT); }
; DEVI void xb_complete(XB& b) {
;     const unsigned G = gridDim.x;
;     unsigned sum, cnt, mine, sp = 0u;
;     for (;;) {
;         sum = 0u; cnt = 0u; mine = 0u;
; #pragma unroll
;         for (unsigned j = 0; j < 16; ++j) { const unsigned c = xb_ld(&b.bar[XB_XCNT(j)]); sum += c; cnt += (c > 0u) ? 1u : 0u; mine = (j == b.x) ? c : mine; }
;         if (sum == G) break;
;         __builtin_amdgcn_s_sleep(1);
;         if ((++sp & 255u) == 0u) { if (xb_ld(&b.bar[XB_TMO])) break; if (sp > XB_SPIN_CAP) { atomicAdd(&b.bar[XB_TMO], 1u); break; } }
;     }
.LBB0_416:
	global_load_dword v15, v16, s[4:5] sc1
	global_load_dword v0, v16, s[6:7] sc1
	global_load_dword v1, v16, s[8:9] sc1
	global_load_dword v2, v16, s[10:11] sc1
	global_load_dword v3, v16, s[12:13] sc1
	global_load_dword v4, v16, s[14:15] sc1
	global_load_dword v5, v16, s[20:21] sc1
	global_load_dword v6, v16, s[22:23] sc1
	global_load_dword v7, v16, s[24:25] sc1
	global_load_dword v8, v16, s[28:29] sc1
	global_load_dword v9, v16, s[30:31] sc1
	global_load_dword v10, v16, s[36:37] sc1
	global_load_dword v11, v16, s[42:43] sc1
	global_load_dword v12, v16, s[50:51] sc1
	global_load_dword v13, v16, s[58:59] sc1
	global_load_dword v14, v16, s[60:61] sc1
	s_mov_b64 s[62:63], -1
	s_mov_b64 s[64:65], -1
	s_waitcnt vmcnt(14)
	v_add_u32_e32 v17, v0, v15
	s_waitcnt vmcnt(13)
	v_add_u32_e32 v17, v17, v1
	s_waitcnt vmcnt(12)
	v_add_u32_e32 v17, v17, v2
	s_waitcnt vmcnt(11)
	v_add_u32_e32 v17, v17, v3
	s_waitcnt vmcnt(10)
	v_add_u32_e32 v17, v17, v4
	s_waitcnt vmcnt(9)
	v_add_u32_e32 v17, v17, v5
	s_waitcnt vmcnt(8)
	v_add_u32_e32 v17, v17, v6
	s_waitcnt vmcnt(7)
	v_add_u32_e32 v17, v17, v7
	s_waitcnt vmcnt(6)
	v_add_u32_e32 v17, v17, v8
	s_waitcnt vmcnt(5)
	v_add_u32_e32 v17, v17, v9
	s_waitcnt vmcnt(4)
	v_add_u32_e32 v17, v17, v10
	s_waitcnt vmcnt(3)
	v_add_u32_e32 v17, v17, v11
	s_waitcnt vmcnt(2)
	v_add_u32_e32 v17, v17, v12
	s_waitcnt vmcnt(1)
	v_add_u32_e32 v17, v17, v13
	s_waitcnt vmcnt(0)
	v_add_u32_e32 v17, v17, v14
	v_cmp_eq_u32_e32 vcc, s27, v17
	s_cbranch_vccnz .LBB0_415
	s_and_b32 s17, s16, 0xff
	s_cmp_eq_u32 s17, 0
	s_mov_b64 s[68:69], -1
	s_sleep 4
	s_cbranch_scc1 .LBB0_420
	s_and_b64 vcc, exec, s[68:69]
	s_cbranch_vccz .LBB0_415

; DEVI unsigned xb_ld(unsigned* p) { return __hip_atomic_load(p, __ATOMIC_RELAXED, __HIP_MEMORY_SCOPE_AGENT); }
; DEVI unsigned xb_add(unsigned* p, unsigned v) { return __hip_atomic_fetch_add(p, v, __ATOMIC_RELAXED, __HIP_MEMORY_SCOPE_AGENT); }
; #define XB_SPIN(cond, bar) do { unsigned _sp = 0; while (cond) { __builtin_amdgcn_s_sleep(1); \
;     if ((++_sp & 255u) == 0u) { if (xb_ld(&(bar)[XB_TMO])) break; if (_sp > XB_SPIN_CAP) { atomicAdd(&(bar)[XB_TMO], 1u); break; } } } } while (0)
; DEVI void gsync(XB& b) {
;     ...
;             const unsigned og = xb_add(&bar[XB_TOP], 1u);
;             const unsigned tg = og / nx;
;             if (og + 1u == (tg + 1u) * nx) xb_add(&bar[XB_TOPGEN], 1u);
;             else XB_SPIN(xb_ld(&bar[XB_TOPGEN]) == tg, bar);
.LBB0_434:
	s_and_b32 s17, s16, 0xff
	s_mov_b64 s[20:21], -1
	s_cmp_lg_u32 s17, 0
	s_mov_b64 s[24:25], -1
	s_sleep 4
	s_cbranch_scc0 .LBB0_437
	s_and_b64 vcc, exec, s[24:25]
	s_cbranch_vccz .LBB0_433

; DEVI unsigned xb_ld(unsigned* p) { return __hip_atomic_load(p, __ATOMIC_RELAXED, __HIP_MEMORY_SCOPE_AGENT); }
; #define XB_SPIN(cond, bar) do { unsigned _sp = 0; while (cond) { __builtin_amdgcn_s_sleep(1); \
;     if ((++_sp & 255u) == 0u) { if (xb_ld(&(bar)[XB_TMO])) break; if (_sp > XB_SPIN_CAP) { atomicAdd(&(bar)[XB_TMO], 1u); break; } } } } while (0)
; DEVI void gsync(XB& b) {
;     ...
;         } else {
;             XB_SPIN(xb_ld(&bar[XB_XGEN(b.x)]) == gen, bar);
.LBB0_451:
	s_and_b32 s17, s16, 0xff
	s_cmp_lg_u32 s17, 0
	s_mov_b64 s[24:25], -1
	s_sleep 4
	s_cbranch_scc0 .LBB0_454
	s_mov_b64 s[28:29], -1
	s_and_b64 vcc, exec, s[24:25]
	s_cbranch_vccz .LBB0_450

; DEVI unsigned xb_ld(unsigned* p) { return __hip_atomic_load(p, __ATOMIC_RELAXED, __HIP_MEMORY_SCOPE_AGENT); }
; DEVI void xb_complete(XB& b) {
;     const unsigned G = gridDim.x;
;     unsigned sum, cnt, mine, sp = 0u;
;     for (;;) {
;         sum = 0u; cnt = 0u; mine = 0u;
; #pragma unroll
;         for (unsigned j = 0; j < 16; ++j) { const unsigned c = xb_ld(&b.bar[XB_XCNT(j)]); sum += c; cnt += (c > 0u) ? 1u : 0u; mine = (j == b.x) ? c : mine; }
;         if (sum == G) break;
;         __builtin_amdgcn_s_sleep(1);
;         if ((++sp & 255u) == 0u) { if (xb_ld(&b.bar[XB_TMO])) break; if (sp > XB_SPIN_CAP) { atomicAdd(&b.bar[XB_TMO], 1u); break; } }
;     }
.LBB0_602:
	global_load_dword v15, v16, s[4:5] sc1
	global_load_dword v0, v16, s[6:7] sc1
	global_load_dword v1, v16, s[8:9] sc1
	global_load_dword v2, v16, s[10:11] sc1
	global_load_dword v3, v16, s[12:13] sc1
	global_load_dword v4, v16, s[14:15] sc1
	global_load_dword v5, v16, s[16:17] sc1
	global_load_dword v6, v16, s[18:19] sc1
	global_load_dword v7, v16, s[20:21] sc1
	global_load_dword v8, v16, s[22:23] sc1
	global_load_dword v9, v16, s[24:25] sc1
	global_load_dword v10, v16, s[30:31] sc1
	global_load_dword v11, v16, s[34:35] sc1
	global_load_dword v12, v16, s[36:37] sc1
	global_load_dword v13, v16, s[42:43] sc1
	global_load_dword v14, v16, s[50:51] sc1
	s_mov_b64 s[58:59], -1
	s_mov_b64 s[60:61], -1
	s_waitcnt vmcnt(14)
	v_add_u32_e32 v17, v0, v15
	s_waitcnt vmcnt(13)
	v_add_u32_e32 v17, v17, v1
	s_waitcnt vmcnt(12)
	v_add_u32_e32 v17, v17, v2
	s_waitcnt vmcnt(11)
	v_add_u32_e32 v17, v17, v3
	s_waitcnt vmcnt(10)
	v_add_u32_e32 v17, v17, v4
	s_waitcnt vmcnt(9)
	v_add_u32_e32 v17, v17, v5
	s_waitcnt vmcnt(8)
	v_add_u32_e32 v17, v17, v6
	s_waitcnt vmcnt(7)
	v_add_u32_e32 v17, v17, v7
	s_waitcnt vmcnt(6)
	v_add_u32_e32 v17, v17, v8
	s_waitcnt vmcnt(5)
	v_add_u32_e32 v17, v17, v9
	s_waitcnt vmcnt(4)
	v_add_u32_e32 v17, v17, v10
	s_waitcnt vmcnt(3)
	v_add_u32_e32 v17, v17, v11
	s_waitcnt vmcnt(2)
	v_add_u32_e32 v17, v17, v12
	s_waitcnt vmcnt(1)
	v_add_u32_e32 v17, v17, v13
	s_waitcnt vmcnt(0)
	v_add_u32_e32 v17, v17, v14
	v_cmp_eq_u32_e32 vcc, s27, v17
	s_cbranch_vccnz .LBB0_601
	s_and_b32 s33, s26, 0xff
	s_cmp_eq_u32 s33, 0
	s_mov_b64 s[62:63], -1
	s_sleep 4
	s_cbranch_scc1 .LBB0_606
	s_and_b64 vcc, exec, s[62:63]
	s_cbranch_vccz .LBB0_601

; DEVI unsigned xb_ld(unsigned* p) { return __hip_atomic_load(p, __ATOMIC_RELAXED, __HIP_MEMORY_SCOPE_AGENT); }
; DEVI void xb_complete(XB& b) {
;     const unsigned G = gridDim.x;
;     unsigned sum, cnt, mine, sp = 0u;
;     for (;;) {
;         sum = 0u; cnt = 0u; mine = 0u;
; #pragma unroll
;         for (unsigned j = 0; j < 16; ++j) { const unsigned c = xb_ld(&b.bar[XB_XCNT(j)]); sum += c; cnt += (c > 0u) ? 1u : 0u; mine = (j == b.x) ? c : mine; }
;         if (sum == G) break;
;         __builtin_amdgcn_s_sleep(1);
;         if ((++sp & 255u) == 0u) { if (xb_ld(&b.bar[XB_TMO])) break; if (sp > XB_SPIN_CAP) { atomicAdd(&b.bar[XB_TMO], 1u); break; } }
;     }
.LBB0_1139:
	global_load_dword v15, v16, s[4:5] sc1
	global_load_dword v0, v16, s[6:7] sc1
	global_load_dword v1, v16, s[8:9] sc1
	global_load_dword v2, v16, s[10:11] sc1
	global_load_dword v3, v16, s[12:13] sc1
	global_load_dword v4, v16, s[14:15] sc1
	global_load_dword v5, v16, s[16:17] sc1
	global_load_dword v6, v16, s[18:19] sc1
	global_load_dword v7, v16, s[20:21] sc1
	global_load_dword v8, v16, s[22:23] sc1
	global_load_dword v9, v16, s[24:25] sc1
	global_load_dword v10, v16, s[30:31] sc1
	global_load_dword v11, v16, s[34:35] sc1
	global_load_dword v12, v16, s[36:37] sc1
	global_load_dword v13, v16, s[38:39] sc1
	global_load_dword v14, v16, s[42:43] sc1
	s_mov_b64 s[50:51], -1
	s_mov_b64 s[58:59], -1
	s_waitcnt vmcnt(14)
	v_add_u32_e32 v17, v0, v15
	s_waitcnt vmcnt(13)
	v_add_u32_e32 v17, v17, v1
	s_waitcnt vmcnt(12)
	v_add_u32_e32 v17, v17, v2
	s_waitcnt vmcnt(11)
	v_add_u32_e32 v17, v17, v3
	s_waitcnt vmcnt(10)
	v_add_u32_e32 v17, v17, v4
	s_waitcnt vmcnt(9)
	v_add_u32_e32 v17, v17, v5
	s_waitcnt vmcnt(8)
	v_add_u32_e32 v17, v17, v6
	s_waitcnt vmcnt(7)
	v_add_u32_e32 v17, v17, v7
	s_waitcnt vmcnt(6)
	v_add_u32_e32 v17, v17, v8
	s_waitcnt vmcnt(5)
	v_add_u32_e32 v17, v17, v9
	s_waitcnt vmcnt(4)
	v_add_u32_e32 v17, v17, v10
	s_waitcnt vmcnt(3)
	v_add_u32_e32 v17, v17, v11
	s_waitcnt vmcnt(2)
	v_add_u32_e32 v17, v17, v12
	s_waitcnt vmcnt(1)
	v_add_u32_e32 v17, v17, v13
	s_waitcnt vmcnt(0)
	v_add_u32_e32 v17, v17, v14
	v_cmp_eq_u32_e32 vcc, s27, v17
	s_cbranch_vccnz .LBB0_1138
	s_and_b32 s33, s26, 0xff
	s_cmp_eq_u32 s33, 0
	s_mov_b64 s[60:61], -1
	s_sleep 4
	s_cbranch_scc1 .LBB0_1143
	s_and_b64 vcc, exec, s[60:61]
	s_cbranch_vccz .LBB0_1138

; DEVI unsigned xb_ld(unsigned* p) { return __hip_atomic_load(p, __ATOMIC_RELAXED, __HIP_MEMORY_SCOPE_AGENT); }
; DEVI void xb_complete(XB& b) {
;     const unsigned G = gridDim.x;
;     unsigned sum, cnt, mine, sp = 0u;
;     for (;;) {
;         sum = 0u; cnt = 0u; mine = 0u;
; #pragma unroll
;         for (unsigned j = 0; j < 16; ++j) { const unsigned c = xb_ld(&b.bar[XB_XCNT(j)]); sum += c; cnt += (c > 0u) ? 1u : 0u; mine = (j == b.x) ? c : mine; }
;         if (sum == G) break;
;         __builtin_amdgcn_s_sleep(1);
;         if ((++sp & 255u) == 0u) { if (xb_ld(&b.bar[XB_TMO])) break; if (sp > XB_SPIN_CAP) { atomicAdd(&b.bar[XB_TMO], 1u); break; } }
;     }
.LBB0_1281:
	global_load_dword v15, v16, s[4:5] sc1
	global_load_dword v0, v16, s[6:7] sc1
	global_load_dword v1, v16, s[8:9] sc1
	global_load_dword v2, v16, s[10:11] sc1
	global_load_dword v3, v16, s[12:13] sc1
	global_load_dword v4, v16, s[14:15] sc1
	global_load_dword v5, v16, s[16:17] sc1
	global_load_dword v6, v16, s[18:19] sc1
	global_load_dword v7, v16, s[20:21] sc1
	global_load_dword v8, v16, s[22:23] sc1
	global_load_dword v9, v16, s[24:25] sc1
	global_load_dword v10, v16, s[30:31] sc1
	global_load_dword v11, v16, s[34:35] sc1
	global_load_dword v12, v16, s[36:37] sc1
	global_load_dword v13, v16, s[38:39] sc1
	global_load_dword v14, v16, s[42:43] sc1
	s_mov_b64 s[46:47], -1
	s_mov_b64 s[50:51], -1
	s_waitcnt vmcnt(14)
	v_add_u32_e32 v17, v0, v15
	s_waitcnt vmcnt(13)
	v_add_u32_e32 v17, v17, v1
	s_waitcnt vmcnt(12)
	v_add_u32_e32 v17, v17, v2
	s_waitcnt vmcnt(11)
	v_add_u32_e32 v17, v17, v3
	s_waitcnt vmcnt(10)
	v_add_u32_e32 v17, v17, v4
	s_waitcnt vmcnt(9)
	v_add_u32_e32 v17, v17, v5
	s_waitcnt vmcnt(8)
	v_add_u32_e32 v17, v17, v6
	s_waitcnt vmcnt(7)
	v_add_u32_e32 v17, v17, v7
	s_waitcnt vmcnt(6)
	v_add_u32_e32 v17, v17, v8
	s_waitcnt vmcnt(5)
	v_add_u32_e32 v17, v17, v9
	s_waitcnt vmcnt(4)
	v_add_u32_e32 v17, v17, v10
	s_waitcnt vmcnt(3)
	v_add_u32_e32 v17, v17, v11
	s_waitcnt vmcnt(2)
	v_add_u32_e32 v17, v17, v12
	s_waitcnt vmcnt(1)
	v_add_u32_e32 v17, v17, v13
	s_waitcnt vmcnt(0)
	v_add_u32_e32 v17, v17, v14
	v_cmp_eq_u32_e32 vcc, s27, v17
	s_cbranch_vccnz .LBB0_1280
	s_and_b32 s33, s26, 0xff
	s_cmp_eq_u32 s33, 0
	s_mov_b64 s[52:53], -1
	s_sleep 4
	s_cbranch_scc1 .LBB0_1285
	s_and_b64 vcc, exec, s[52:53]
	s_cbranch_vccz .LBB0_1280

; DEVI unsigned xb_ld(unsigned* p) { return __hip_atomic_load(p, __ATOMIC_RELAXED, __HIP_MEMORY_SCOPE_AGENT); }
; DEVI void xb_complete(XB& b) {
;     const unsigned G = gridDim.x;
;     unsigned sum, cnt, mine, sp = 0u;
;     for (;;) {
;         sum = 0u; cnt = 0u; mine = 0u;
; #pragma unroll
;         for (unsigned j = 0; j < 16; ++j) { const unsigned c = xb_ld(&b.bar[XB_XCNT(j)]); sum += c; cnt += (c > 0u) ? 1u : 0u; mine = (j == b.x) ? c : mine; }
;         if (sum == G) break;
;         __builtin_amdgcn_s_sleep(1);
;         if ((++sp & 255u) == 0u) { if (xb_ld(&b.bar[XB_TMO])) break; if (sp > XB_SPIN_CAP) { atomicAdd(&b.bar[XB_TMO], 1u); break; } }
;     }
.LBB0_1378:
	global_load_dword v15, v16, s[6:7] sc1
	global_load_dword v0, v16, s[8:9] sc1
	global_load_dword v1, v16, s[10:11] sc1
	global_load_dword v2, v16, s[12:13] sc1
	global_load_dword v3, v16, s[14:15] sc1
	global_load_dword v4, v16, s[16:17] sc1
	global_load_dword v5, v16, s[18:19] sc1
	global_load_dword v6, v16, s[20:21] sc1
	global_load_dword v7, v16, s[22:23] sc1
	global_load_dword v8, v16, s[24:25] sc1
	global_load_dword v9, v16, s[28:29] sc1
	global_load_dword v10, v16, s[34:35] sc1
	global_load_dword v11, v16, s[36:37] sc1
	global_load_dword v12, v16, s[38:39] sc1
	global_load_dword v13, v16, s[42:43] sc1
	global_load_dword v14, v16, s[46:47] sc1
	s_mov_b64 s[50:51], -1
	s_mov_b64 s[52:53], -1
	s_waitcnt vmcnt(14)
	v_add_u32_e32 v17, v0, v15
	s_waitcnt vmcnt(13)
	v_add_u32_e32 v17, v17, v1
	s_waitcnt vmcnt(12)
	v_add_u32_e32 v17, v17, v2
	s_waitcnt vmcnt(11)
	v_add_u32_e32 v17, v17, v3
	s_waitcnt vmcnt(10)
	v_add_u32_e32 v17, v17, v4
	s_waitcnt vmcnt(9)
	v_add_u32_e32 v17, v17, v5
	s_waitcnt vmcnt(8)
	v_add_u32_e32 v17, v17, v6
	s_waitcnt vmcnt(7)
	v_add_u32_e32 v17, v17, v7
	s_waitcnt vmcnt(6)
	v_add_u32_e32 v17, v17, v8
	s_waitcnt vmcnt(5)
	v_add_u32_e32 v17, v17, v9
	s_waitcnt vmcnt(4)
	v_add_u32_e32 v17, v17, v10
	s_waitcnt vmcnt(3)
	v_add_u32_e32 v17, v17, v11
	s_waitcnt vmcnt(2)
	v_add_u32_e32 v17, v17, v12
	s_waitcnt vmcnt(1)
	v_add_u32_e32 v17, v17, v13
	s_waitcnt vmcnt(0)
	v_add_u32_e32 v17, v17, v14
	v_cmp_eq_u32_e32 vcc, s27, v17
	s_cbranch_vccnz .LBB0_1377
	s_and_b32 s33, s26, 0xff
	s_cmp_eq_u32 s33, 0
	s_mov_b64 s[56:57], -1
	s_sleep 4
	s_cbranch_scc1 .LBB0_1382
	s_and_b64 vcc, exec, s[56:57]
	s_cbranch_vccz .LBB0_1377

; DEVI unsigned xb_ld(unsigned* p) { return __hip_atomic_load(p, __ATOMIC_RELAXED, __HIP_MEMORY_SCOPE_AGENT); }
; DEVI unsigned xb_add(unsigned* p, unsigned v) { return __hip_atomic_fetch_add(p, v, __ATOMIC_RELAXED, __HIP_MEMORY_SCOPE_AGENT); }
; #define XB_SPIN(cond, bar) do { unsigned _sp = 0; while (cond) { __builtin_amdgcn_s_sleep(1); \
;     if ((++_sp & 255u) == 0u) { if (xb_ld(&(bar)[XB_TMO])) break; if (_sp > XB_SPIN_CAP) { atomicAdd(&(bar)[XB_TMO], 1u); break; } } } } while (0)
; DEVI void gsync(XB& b) {
;     ...
;             const unsigned og = xb_add(&bar[XB_TOP], 1u);
;             const unsigned tg = og / nx;
;             if (og + 1u == (tg + 1u) * nx) xb_add(&bar[XB_TOPGEN], 1u);
;             else XB_SPIN(xb_ld(&bar[XB_TOPGEN]) == tg, bar);
.LBB0_1396:
	s_and_b32 s20, s24, 0xff
	s_mov_b64 s[18:19], -1
	s_cmp_lg_u32 s20, 0
	s_mov_b64 s[22:23], -1
	s_sleep 4
	s_cbranch_scc0 .LBB0_1399
	s_and_b64 vcc, exec, s[22:23]
	s_cbranch_vccz .LBB0_1395

; DEVI unsigned xb_ld(unsigned* p) { return __hip_atomic_load(p, __ATOMIC_RELAXED, __HIP_MEMORY_SCOPE_AGENT); }
; #define XB_SPIN(cond, bar) do { unsigned _sp = 0; while (cond) { __builtin_amdgcn_s_sleep(1); \
;     if ((++_sp & 255u) == 0u) { if (xb_ld(&(bar)[XB_TMO])) break; if (_sp > XB_SPIN_CAP) { atomicAdd(&(bar)[XB_TMO], 1u); break; } } } } while (0)
; DEVI void gsync(XB& b) {
;     ...
;         } else {
;             XB_SPIN(xb_ld(&bar[XB_XGEN(b.x)]) == gen, bar);
.LBB0_1413:
	s_and_b32 s20, s26, 0xff
	s_cmp_lg_u32 s20, 0
	s_mov_b64 s[22:23], -1
	s_sleep 4
	s_cbranch_scc0 .LBB0_1416
	s_mov_b64 s[24:25], -1
	s_and_b64 vcc, exec, s[22:23]
	s_cbranch_vccz .LBB0_1412

; DEVI unsigned xb_ld(unsigned* p) { return __hip_atomic_load(p, __ATOMIC_RELAXED, __HIP_MEMORY_SCOPE_AGENT); }
; DEVI void xb_complete(XB& b) {
;     const unsigned G = gridDim.x;
;     unsigned sum, cnt, mine, sp = 0u;
;     for (;;) {
;         sum = 0u; cnt = 0u; mine = 0u;
; #pragma unroll
;         for (unsigned j = 0; j < 16; ++j) { const unsigned c = xb_ld(&b.bar[XB_XCNT(j)]); sum += c; cnt += (c > 0u) ? 1u : 0u; mine = (j == b.x) ? c : mine; }
;         if (sum == G) break;
;         __builtin_amdgcn_s_sleep(1);
;         if ((++sp & 255u) == 0u) { if (xb_ld(&b.bar[XB_TMO])) break; if (sp > XB_SPIN_CAP) { atomicAdd(&b.bar[XB_TMO], 1u); break; } }
;     }
.LBB0_1448:
	global_load_dword v15, v16, s[4:5] sc1
	global_load_dword v0, v16, s[6:7] sc1
	global_load_dword v1, v16, s[8:9] sc1
	global_load_dword v2, v16, s[10:11] sc1
	global_load_dword v3, v16, s[12:13] sc1
	global_load_dword v4, v16, s[14:15] sc1
	global_load_dword v5, v16, s[16:17] sc1
	global_load_dword v6, v16, s[18:19] sc1
	global_load_dword v7, v16, s[20:21] sc1
	global_load_dword v8, v16, s[22:23] sc1
	global_load_dword v9, v16, s[24:25] sc1
	global_load_dword v10, v16, s[30:31] sc1
	global_load_dword v11, v16, s[34:35] sc1
	global_load_dword v12, v16, s[36:37] sc1
	global_load_dword v13, v16, s[38:39] sc1
	global_load_dword v14, v16, s[42:43] sc1
	s_mov_b64 s[44:45], -1
	s_mov_b64 s[46:47], -1
	s_waitcnt vmcnt(14)
	v_add_u32_e32 v17, v0, v15
	s_waitcnt vmcnt(13)
	v_add_u32_e32 v17, v17, v1
	s_waitcnt vmcnt(12)
	v_add_u32_e32 v17, v17, v2
	s_waitcnt vmcnt(11)
	v_add_u32_e32 v17, v17, v3
	s_waitcnt vmcnt(10)
	v_add_u32_e32 v17, v17, v4
	s_waitcnt vmcnt(9)
	v_add_u32_e32 v17, v17, v5
	s_waitcnt vmcnt(8)
	v_add_u32_e32 v17, v17, v6
	s_waitcnt vmcnt(7)
	v_add_u32_e32 v17, v17, v7
	s_waitcnt vmcnt(6)
	v_add_u32_e32 v17, v17, v8
	s_waitcnt vmcnt(5)
	v_add_u32_e32 v17, v17, v9
	s_waitcnt vmcnt(4)
	v_add_u32_e32 v17, v17, v10
	s_waitcnt vmcnt(3)
	v_add_u32_e32 v17, v17, v11
	s_waitcnt vmcnt(2)
	v_add_u32_e32 v17, v17, v12
	s_waitcnt vmcnt(1)
	v_add_u32_e32 v17, v17, v13
	s_waitcnt vmcnt(0)
	v_add_u32_e32 v17, v17, v14
	v_cmp_eq_u32_e32 vcc, s27, v17
	s_cbranch_vccnz .LBB0_1447
	s_and_b32 s33, s26, 0xff
	s_cmp_eq_u32 s33, 0
	s_mov_b64 s[50:51], -1
	s_sleep 4
	s_cbranch_scc1 .LBB0_1452
	s_and_b64 vcc, exec, s[50:51]
	s_cbranch_vccz .LBB0_1447

; DEVI unsigned xb_ld(unsigned* p) { return __hip_atomic_load(p, __ATOMIC_RELAXED, __HIP_MEMORY_SCOPE_AGENT); }
; #define XB_SPIN(cond, bar) do { unsigned _sp = 0; while (cond) { __builtin_amdgcn_s_sleep(1); \
;     if ((++_sp & 255u) == 0u) { if (xb_ld(&(bar)[XB_TMO])) break; if (_sp > XB_SPIN_CAP) { atomicAdd(&(bar)[XB_TMO], 1u); break; } } } } while (0)
; DEVI void gsync(XB& b) {
;     ...
;         } else {
;             XB_SPIN(xb_ld(&bar[XB_XGEN(b.x)]) == gen, bar);
.LBB0_1545:
	s_and_b32 s16, s22, 0xff
	s_cmp_lg_u32 s16, 0
	s_mov_b64 s[18:19], -1
	s_sleep 4
	s_cbranch_scc0 .LBB0_1548
	s_mov_b64 s[20:21], -1
	s_and_b64 vcc, exec, s[18:19]
	s_cbranch_vccz .LBB0_1544
